# D unit static priority raise for waves 0-3 instead of 4-7
# speedup vs baseline: 1.0075x; 1.0075x over previous
; __device__ __forceinline__ unsigned xb_xcc_id() { return (unsigned)__builtin_amdgcn_s_getreg((3 << 11) | 20) & 0xFu; }
; __global__ void __launch_bounds__(NT, 2) fwd(Args args) {
;     ...
;             if (tid == 0) { const unsigned myx = xb_xcc_id() & 7u; int got = -1;
;                 for (unsigned k = 0; k < 8u && got < 0; ++k) { const unsigned x = (myx + k) & 7u;
;                     const unsigned v = __hip_atomic_fetch_add(ctl + CW_QD + ((pass * 2 + r2) * 8 + x) * 64, 1u, RLX_AGENT); if (v < 32u) got = (int)(x * 32u + v); }
;                 *slot = got; }
;             __syncthreads();
;             const int u = __builtin_amdgcn_readfirstlane(*slot); if (u < 0) break;
;             unit_dilated2(u, QB, KB, VB, GB, MIX, lds, tid, lane, wave); }
.LBB0_752:
	s_or_b64 exec, exec, s[6:7]
	v_mov_b32_e32 v3, s49
	s_waitcnt lgkmcnt(0)
	s_barrier
	ds_read_b32 v3, v3
	s_waitcnt lgkmcnt(0)
	v_readfirstlane_b32 s0, v3
	s_cmp_lt_i32 s0, 0
	s_cbranch_scc1 .LBB0_786
	s_cmp_gt_u32 s33, 3
	s_cbranch_scc1 .Ldprio_lo
	s_setprio 2
